# grid barrier: non-leader workgroups poll the cross-XCC release generation directly (skip per-XCC release hop)
# speedup vs baseline: 1.0067x; 1.0067x over previous
.LBB0_2174:
	s_or_b64 exec, exec, s[26:27]
	v_cvt_f32_u32_e32 v5, v3
	s_waitcnt vmcnt(0)
	v_readfirstlane_b32 s2, v4
	v_sub_u32_e32 v4, 0, v3
	v_rcp_iflag_f32_e32 v5, v5
	v_add_u32_e32 v6, s2, v0
	v_mul_f32_e32 v5, 0x4f7ffffe, v5
	v_cvt_u32_f32_e32 v5, v5
	v_mul_lo_u32 v0, v4, v5
	v_mul_hi_u32 v0, v5, v0
	v_add_u32_e32 v0, v5, v0
	v_mul_hi_u32 v0, v6, v0
	v_mul_lo_u32 v4, v0, v3
	v_sub_u32_e32 v4, v6, v4
	v_add_u32_e32 v5, 1, v0
	v_cmp_ge_u32_e32 vcc, v4, v3
	s_nop 1
	v_cndmask_b32_e32 v0, v0, v5, vcc
	v_sub_u32_e32 v5, v4, v3
	v_cndmask_b32_e32 v4, v4, v5, vcc
	v_add_u32_e32 v5, 1, v0
	v_cmp_ge_u32_e32 vcc, v4, v3
	v_add_u32_e32 v4, 1, v6
	s_nop 0
	v_cndmask_b32_e32 v0, v0, v5, vcc
	v_mul_lo_u32 v5, v3, v0
	v_add_u32_e32 v3, v5, v3
	v_cmp_ne_u32_e32 vcc, v4, v3
	s_and_saveexec_b64 s[2:3], vcc
	s_xor_b64 s[26:27], exec, s[2:3]
	s_cbranch_execz .LBB0_2188
	v_readlane_b32 s2, v253, 32
	v_readlane_b32 s3, v253, 33
	s_waitcnt lgkmcnt(0)
	s_nop 3
	global_load_dword v2, v1, s[2:3] sc1
	s_waitcnt vmcnt(0)
	v_cmp_eq_u32_e32 vcc, v2, v0
	s_and_saveexec_b64 s[30:31], vcc
	s_cbranch_execz .LBB0_2187
	s_mov_b32 s33, 1
	s_mov_b64 s[34:35], 0
	s_branch .LBB0_2178
